# hand-scheduled SwiGLU epilogues (8-way interleaved exp/rcp chains, scalar f32 FMAs instead of packed, v_rsq_f32 for the row rstd) in both gate|up GEMMs
# speedup vs baseline: 1.0072x; 1.0072x over previous
.LBB0_780:
	v_lshl_or_b32 v224, s0, 7, v181
	v_lshl_add_u32 v223, v1, 2, s1
	ds_read_b32 v206, v223
	ds_read_b32 v208, v223 offset:64
	ds_read_b32 v210, v223 offset:128
	ds_read_b32 v212, v223 offset:192
	ds_read_b32 v214, v223 offset:512
	ds_read_b32 v216, v223 offset:576
	ds_read_b32 v218, v223 offset:640
	ds_read_b32 v220, v223 offset:704
	s_lshl_b32 s12, s49, 2
	s_add_i32 s12, s1, s12
	v_lshl_add_u32 v222, v172, 2, s12
	s_lshl_b32 s11, s10, 8
	ds_read_b128 v[62:65], v222 offset:1024
	ds_read_b128 v[58:61], v222 offset:1040
	ds_read_b128 v[54:57], v222 offset:1536
	ds_read_b128 v[50:53], v222 offset:1552
	v_ashrrev_i32_e32 v225, 31, v224
	v_lshlrev_b64 v[224:225], 1, v[224:225]
	v_lshl_add_u64 v[224:225], s[20:21], 0, v[224:225]
	s_waitcnt lgkmcnt(4)
	v_fmamk_f32 v206, v206, 0x3a800000, v185
	v_fmamk_f32 v208, v208, 0x3a800000, v185
	v_fmamk_f32 v210, v210, 0x3a800000, v185
	v_fmamk_f32 v212, v212, 0x3a800000, v185
	v_fmamk_f32 v214, v214, 0x3a800000, v185
	v_fmamk_f32 v216, v216, 0x3a800000, v185
	v_fmamk_f32 v218, v218, 0x3a800000, v185
	v_fmamk_f32 v220, v220, 0x3a800000, v185
	v_rsq_f32_e32 v206, v206
	v_rsq_f32_e32 v208, v208
	v_rsq_f32_e32 v210, v210
	v_rsq_f32_e32 v212, v212
	v_rsq_f32_e32 v214, v214
	v_rsq_f32_e32 v216, v216
	v_rsq_f32_e32 v218, v218
	v_rsq_f32_e32 v220, v220
	s_waitcnt lgkmcnt(0)
	v_fma_f32 v142, v142, v206, v62
	v_fma_f32 v143, v143, v206, v63
	v_fma_f32 v144, v144, v206, v64
	v_fma_f32 v145, v145, v206, v65
	v_fma_f32 v138, v138, v206, v58
	v_fma_f32 v139, v139, v206, v59
	v_fma_f32 v140, v140, v206, v60
	v_fma_f32 v141, v141, v206, v61
	v_mul_f32_e32 v190, 0xbfb8aa3b, v142
	v_mul_f32_e32 v191, 0xbfb8aa3b, v143
	v_mul_f32_e32 v192, 0xbfb8aa3b, v144
	v_mul_f32_e32 v193, 0xbfb8aa3b, v145
	v_mul_f32_e32 v194, 0xbfb8aa3b, v138
	v_mul_f32_e32 v195, 0xbfb8aa3b, v139
	v_mul_f32_e32 v196, 0xbfb8aa3b, v140
	v_mul_f32_e32 v197, 0xbfb8aa3b, v141
	v_fma_f32 v134, v134, v206, v54
	v_fma_f32 v135, v135, v206, v55
	v_fma_f32 v136, v136, v206, v56
	v_fma_f32 v137, v137, v206, v57
	v_fma_f32 v130, v130, v206, v50
	v_fma_f32 v131, v131, v206, v51
	v_fma_f32 v132, v132, v206, v52
	v_fma_f32 v133, v133, v206, v53
	v_exp_f32_e32 v190, v190
	v_exp_f32_e32 v191, v191
	v_exp_f32_e32 v192, v192
	v_exp_f32_e32 v193, v193
	v_exp_f32_e32 v194, v194
	v_exp_f32_e32 v195, v195
	v_exp_f32_e32 v196, v196
	v_exp_f32_e32 v197, v197
	v_add_u32_e32 v226, s11, v1
	v_mad_i64_i32 v[226:227], s[12:13], v226, s90, v[224:225]
	v_add_f32_e32 v190, 1.0, v190
	v_add_f32_e32 v191, 1.0, v191
	v_add_f32_e32 v192, 1.0, v192
	v_add_f32_e32 v193, 1.0, v193
	v_add_f32_e32 v194, 1.0, v194
	v_add_f32_e32 v195, 1.0, v195
	v_add_f32_e32 v196, 1.0, v196
	v_add_f32_e32 v197, 1.0, v197
	v_rcp_f32_e32 v190, v190
	v_rcp_f32_e32 v191, v191
	v_rcp_f32_e32 v192, v192
	v_rcp_f32_e32 v193, v193
	v_rcp_f32_e32 v194, v194
	v_rcp_f32_e32 v195, v195
	v_rcp_f32_e32 v196, v196
	v_rcp_f32_e32 v197, v197
	v_mul_f32_e32 v142, v142, v190
	v_mul_f32_e32 v143, v143, v191
	v_mul_f32_e32 v144, v144, v192
	v_mul_f32_e32 v145, v145, v193
	v_mul_f32_e32 v138, v138, v194
	v_mul_f32_e32 v139, v139, v195
	v_mul_f32_e32 v140, v140, v196
	v_mul_f32_e32 v141, v141, v197
	v_mul_f32_e32 v142, v134, v142
	v_mul_f32_e32 v143, v135, v143
	v_mul_f32_e32 v144, v136, v144
	v_mul_f32_e32 v145, v137, v145
	v_mul_f32_e32 v138, v130, v138
	v_mul_f32_e32 v139, v131, v139
	v_mul_f32_e32 v140, v132, v140
	v_mul_f32_e32 v141, v133, v141
	v_cvt_pk_bf16_f32 v198, v142, v143
	v_cvt_pk_bf16_f32 v199, v144, v145
	v_cvt_pk_bf16_f32 v200, v138, v139
	v_cvt_pk_bf16_f32 v201, v140, v141
	global_store_dwordx4 v[226:227], v[198:201], off
	v_fma_f32 v126, v126, v208, v62
	v_fma_f32 v127, v127, v208, v63
	v_fma_f32 v128, v128, v208, v64
	v_fma_f32 v129, v129, v208, v65
	v_fma_f32 v122, v122, v208, v58
	v_fma_f32 v123, v123, v208, v59
	v_fma_f32 v124, v124, v208, v60
	v_fma_f32 v125, v125, v208, v61
	v_mul_f32_e32 v190, 0xbfb8aa3b, v126
	v_mul_f32_e32 v191, 0xbfb8aa3b, v127
	v_mul_f32_e32 v192, 0xbfb8aa3b, v128
	v_mul_f32_e32 v193, 0xbfb8aa3b, v129
	v_mul_f32_e32 v194, 0xbfb8aa3b, v122
	v_mul_f32_e32 v195, 0xbfb8aa3b, v123
	v_mul_f32_e32 v196, 0xbfb8aa3b, v124
	v_mul_f32_e32 v197, 0xbfb8aa3b, v125
	v_fma_f32 v118, v118, v208, v54
	v_fma_f32 v119, v119, v208, v55
	v_fma_f32 v120, v120, v208, v56
	v_fma_f32 v121, v121, v208, v57
	v_fma_f32 v114, v114, v208, v50
	v_fma_f32 v115, v115, v208, v51
	v_fma_f32 v116, v116, v208, v52
	v_fma_f32 v117, v117, v208, v53
	v_exp_f32_e32 v190, v190
	v_exp_f32_e32 v191, v191
	v_exp_f32_e32 v192, v192
	v_exp_f32_e32 v193, v193
	v_exp_f32_e32 v194, v194
	v_exp_f32_e32 v195, v195
	v_exp_f32_e32 v196, v196
	v_exp_f32_e32 v197, v197
	v_add_u32_e32 v228, s11, v174
	v_mad_i64_i32 v[228:229], s[12:13], v228, s90, v[224:225]
	v_add_f32_e32 v190, 1.0, v190
	v_add_f32_e32 v191, 1.0, v191
	v_add_f32_e32 v192, 1.0, v192
	v_add_f32_e32 v193, 1.0, v193
	v_add_f32_e32 v194, 1.0, v194
	v_add_f32_e32 v195, 1.0, v195
	v_add_f32_e32 v196, 1.0, v196
	v_add_f32_e32 v197, 1.0, v197
	v_rcp_f32_e32 v190, v190
	v_rcp_f32_e32 v191, v191
	v_rcp_f32_e32 v192, v192
	v_rcp_f32_e32 v193, v193
	v_rcp_f32_e32 v194, v194
	v_rcp_f32_e32 v195, v195
	v_rcp_f32_e32 v196, v196
	v_rcp_f32_e32 v197, v197
	v_mul_f32_e32 v126, v126, v190
	v_mul_f32_e32 v127, v127, v191
	v_mul_f32_e32 v128, v128, v192
	v_mul_f32_e32 v129, v129, v193
	v_mul_f32_e32 v122, v122, v194
	v_mul_f32_e32 v123, v123, v195
	v_mul_f32_e32 v124, v124, v196
	v_mul_f32_e32 v125, v125, v197
	v_mul_f32_e32 v126, v118, v126
	v_mul_f32_e32 v127, v119, v127
	v_mul_f32_e32 v128, v120, v128
	v_mul_f32_e32 v129, v121, v129
	v_mul_f32_e32 v122, v114, v122
	v_mul_f32_e32 v123, v115, v123
	v_mul_f32_e32 v124, v116, v124
	v_mul_f32_e32 v125, v117, v125
	v_cvt_pk_bf16_f32 v202, v126, v127
	v_cvt_pk_bf16_f32 v203, v128, v129
	v_cvt_pk_bf16_f32 v204, v122, v123
	v_cvt_pk_bf16_f32 v205, v124, v125
	global_store_dwordx4 v[228:229], v[202:205], off
	v_fma_f32 v110, v110, v210, v62
	v_fma_f32 v111, v111, v210, v63
	v_fma_f32 v112, v112, v210, v64
	v_fma_f32 v113, v113, v210, v65
	v_fma_f32 v106, v106, v210, v58
	v_fma_f32 v107, v107, v210, v59
	v_fma_f32 v108, v108, v210, v60
	v_fma_f32 v109, v109, v210, v61
	v_mul_f32_e32 v190, 0xbfb8aa3b, v110
	v_mul_f32_e32 v191, 0xbfb8aa3b, v111
	v_mul_f32_e32 v192, 0xbfb8aa3b, v112
	v_mul_f32_e32 v193, 0xbfb8aa3b, v113
	v_mul_f32_e32 v194, 0xbfb8aa3b, v106
	v_mul_f32_e32 v195, 0xbfb8aa3b, v107
	v_mul_f32_e32 v196, 0xbfb8aa3b, v108
	v_mul_f32_e32 v197, 0xbfb8aa3b, v109
	v_fma_f32 v102, v102, v210, v54
	v_fma_f32 v103, v103, v210, v55
	v_fma_f32 v104, v104, v210, v56
	v_fma_f32 v105, v105, v210, v57
	v_fma_f32 v98, v98, v210, v50
	v_fma_f32 v99, v99, v210, v51
	v_fma_f32 v100, v100, v210, v52
	v_fma_f32 v101, v101, v210, v53
	v_exp_f32_e32 v190, v190
	v_exp_f32_e32 v191, v191
	v_exp_f32_e32 v192, v192
	v_exp_f32_e32 v193, v193
	v_exp_f32_e32 v194, v194
	v_exp_f32_e32 v195, v195
	v_exp_f32_e32 v196, v196
	v_exp_f32_e32 v197, v197
	v_add_u32_e32 v226, s11, v175
	v_mad_i64_i32 v[226:227], s[12:13], v226, s90, v[224:225]
	v_add_f32_e32 v190, 1.0, v190
	v_add_f32_e32 v191, 1.0, v191
	v_add_f32_e32 v192, 1.0, v192
	v_add_f32_e32 v193, 1.0, v193
	v_add_f32_e32 v194, 1.0, v194
	v_add_f32_e32 v195, 1.0, v195
	v_add_f32_e32 v196, 1.0, v196
	v_add_f32_e32 v197, 1.0, v197
	v_rcp_f32_e32 v190, v190
	v_rcp_f32_e32 v191, v191
	v_rcp_f32_e32 v192, v192
	v_rcp_f32_e32 v193, v193
	v_rcp_f32_e32 v194, v194
	v_rcp_f32_e32 v195, v195
	v_rcp_f32_e32 v196, v196
	v_rcp_f32_e32 v197, v197
	v_mul_f32_e32 v110, v110, v190
	v_mul_f32_e32 v111, v111, v191
	v_mul_f32_e32 v112, v112, v192
	v_mul_f32_e32 v113, v113, v193
	v_mul_f32_e32 v106, v106, v194
	v_mul_f32_e32 v107, v107, v195
	v_mul_f32_e32 v108, v108, v196
	v_mul_f32_e32 v109, v109, v197
	v_mul_f32_e32 v110, v102, v110
	v_mul_f32_e32 v111, v103, v111
	v_mul_f32_e32 v112, v104, v112
	v_mul_f32_e32 v113, v105, v113
	v_mul_f32_e32 v106, v98, v106
	v_mul_f32_e32 v107, v99, v107
	v_mul_f32_e32 v108, v100, v108
	v_mul_f32_e32 v109, v101, v109
	v_cvt_pk_bf16_f32 v198, v110, v111
	v_cvt_pk_bf16_f32 v199, v112, v113
	v_cvt_pk_bf16_f32 v200, v106, v107
	v_cvt_pk_bf16_f32 v201, v108, v109
	global_store_dwordx4 v[226:227], v[198:201], off
	v_fma_f32 v94, v94, v212, v62
	v_fma_f32 v95, v95, v212, v63
	v_fma_f32 v96, v96, v212, v64
	v_fma_f32 v97, v97, v212, v65
	v_fma_f32 v90, v90, v212, v58
	v_fma_f32 v91, v91, v212, v59
	v_fma_f32 v92, v92, v212, v60
	v_fma_f32 v93, v93, v212, v61
	v_mul_f32_e32 v190, 0xbfb8aa3b, v94
	v_mul_f32_e32 v191, 0xbfb8aa3b, v95
	v_mul_f32_e32 v192, 0xbfb8aa3b, v96
	v_mul_f32_e32 v193, 0xbfb8aa3b, v97
	v_mul_f32_e32 v194, 0xbfb8aa3b, v90
	v_mul_f32_e32 v195, 0xbfb8aa3b, v91
	v_mul_f32_e32 v196, 0xbfb8aa3b, v92
	v_mul_f32_e32 v197, 0xbfb8aa3b, v93
	v_fma_f32 v86, v86, v212, v54
	v_fma_f32 v87, v87, v212, v55
	v_fma_f32 v88, v88, v212, v56
	v_fma_f32 v89, v89, v212, v57
	v_fma_f32 v82, v82, v212, v50
	v_fma_f32 v83, v83, v212, v51
	v_fma_f32 v84, v84, v212, v52
	v_fma_f32 v85, v85, v212, v53
	v_exp_f32_e32 v190, v190
	v_exp_f32_e32 v191, v191
	v_exp_f32_e32 v192, v192
	v_exp_f32_e32 v193, v193
	v_exp_f32_e32 v194, v194
	v_exp_f32_e32 v195, v195
	v_exp_f32_e32 v196, v196
	v_exp_f32_e32 v197, v197
	v_add_u32_e32 v228, s11, v176
	v_mad_i64_i32 v[228:229], s[12:13], v228, s90, v[224:225]
	v_add_f32_e32 v190, 1.0, v190
	v_add_f32_e32 v191, 1.0, v191
	v_add_f32_e32 v192, 1.0, v192
	v_add_f32_e32 v193, 1.0, v193
	v_add_f32_e32 v194, 1.0, v194
	v_add_f32_e32 v195, 1.0, v195
	v_add_f32_e32 v196, 1.0, v196
	v_add_f32_e32 v197, 1.0, v197
	v_rcp_f32_e32 v190, v190
	v_rcp_f32_e32 v191, v191
	v_rcp_f32_e32 v192, v192
	v_rcp_f32_e32 v193, v193
	v_rcp_f32_e32 v194, v194
	v_rcp_f32_e32 v195, v195
	v_rcp_f32_e32 v196, v196
	v_rcp_f32_e32 v197, v197
	v_mul_f32_e32 v94, v94, v190
	v_mul_f32_e32 v95, v95, v191
	v_mul_f32_e32 v96, v96, v192
	v_mul_f32_e32 v97, v97, v193
	v_mul_f32_e32 v90, v90, v194
	v_mul_f32_e32 v91, v91, v195
	v_mul_f32_e32 v92, v92, v196
	v_mul_f32_e32 v93, v93, v197
	v_mul_f32_e32 v94, v86, v94
	v_mul_f32_e32 v95, v87, v95
	v_mul_f32_e32 v96, v88, v96
	v_mul_f32_e32 v97, v89, v97
	v_mul_f32_e32 v90, v82, v90
	v_mul_f32_e32 v91, v83, v91
	v_mul_f32_e32 v92, v84, v92
	v_mul_f32_e32 v93, v85, v93
	v_cvt_pk_bf16_f32 v202, v94, v95
	v_cvt_pk_bf16_f32 v203, v96, v97
	v_cvt_pk_bf16_f32 v204, v90, v91
	v_cvt_pk_bf16_f32 v205, v92, v93
	global_store_dwordx4 v[228:229], v[202:205], off
	v_fma_f32 v78, v78, v214, v62
	v_fma_f32 v79, v79, v214, v63
	v_fma_f32 v80, v80, v214, v64
	v_fma_f32 v81, v81, v214, v65
	v_fma_f32 v74, v74, v214, v58
	v_fma_f32 v75, v75, v214, v59
	v_fma_f32 v76, v76, v214, v60
	v_fma_f32 v77, v77, v214, v61
	v_mul_f32_e32 v190, 0xbfb8aa3b, v78
	v_mul_f32_e32 v191, 0xbfb8aa3b, v79
	v_mul_f32_e32 v192, 0xbfb8aa3b, v80
	v_mul_f32_e32 v193, 0xbfb8aa3b, v81
	v_mul_f32_e32 v194, 0xbfb8aa3b, v74
	v_mul_f32_e32 v195, 0xbfb8aa3b, v75
	v_mul_f32_e32 v196, 0xbfb8aa3b, v76
	v_mul_f32_e32 v197, 0xbfb8aa3b, v77
	v_fma_f32 v70, v70, v214, v54
	v_fma_f32 v71, v71, v214, v55
	v_fma_f32 v72, v72, v214, v56
	v_fma_f32 v73, v73, v214, v57
	v_fma_f32 v66, v66, v214, v50
	v_fma_f32 v67, v67, v214, v51
	v_fma_f32 v68, v68, v214, v52
	v_fma_f32 v69, v69, v214, v53
	v_exp_f32_e32 v190, v190
	v_exp_f32_e32 v191, v191
	v_exp_f32_e32 v192, v192
	v_exp_f32_e32 v193, v193
	v_exp_f32_e32 v194, v194
	v_exp_f32_e32 v195, v195
	v_exp_f32_e32 v196, v196
	v_exp_f32_e32 v197, v197
	v_add_u32_e32 v226, s11, v177
	v_mad_i64_i32 v[226:227], s[12:13], v226, s90, v[224:225]
	v_add_f32_e32 v190, 1.0, v190
	v_add_f32_e32 v191, 1.0, v191
	v_add_f32_e32 v192, 1.0, v192
	v_add_f32_e32 v193, 1.0, v193
	v_add_f32_e32 v194, 1.0, v194
	v_add_f32_e32 v195, 1.0, v195
	v_add_f32_e32 v196, 1.0, v196
	v_add_f32_e32 v197, 1.0, v197
	v_rcp_f32_e32 v190, v190
	v_rcp_f32_e32 v191, v191
	v_rcp_f32_e32 v192, v192
	v_rcp_f32_e32 v193, v193
	v_rcp_f32_e32 v194, v194
	v_rcp_f32_e32 v195, v195
	v_rcp_f32_e32 v196, v196
	v_rcp_f32_e32 v197, v197
	v_mul_f32_e32 v78, v78, v190
	v_mul_f32_e32 v79, v79, v191
	v_mul_f32_e32 v80, v80, v192
	v_mul_f32_e32 v81, v81, v193
	v_mul_f32_e32 v74, v74, v194
	v_mul_f32_e32 v75, v75, v195
	v_mul_f32_e32 v76, v76, v196
	v_mul_f32_e32 v77, v77, v197
	v_mul_f32_e32 v78, v70, v78
	v_mul_f32_e32 v79, v71, v79
	v_mul_f32_e32 v80, v72, v80
	v_mul_f32_e32 v81, v73, v81
	v_mul_f32_e32 v74, v66, v74
	v_mul_f32_e32 v75, v67, v75
	v_mul_f32_e32 v76, v68, v76
	v_mul_f32_e32 v77, v69, v77
	v_cvt_pk_bf16_f32 v198, v78, v79
	v_cvt_pk_bf16_f32 v199, v80, v81
	v_cvt_pk_bf16_f32 v200, v74, v75
	v_cvt_pk_bf16_f32 v201, v76, v77
	global_store_dwordx4 v[226:227], v[198:201], off
	v_fma_f32 v46, v46, v216, v62
	v_fma_f32 v47, v47, v216, v63
	v_fma_f32 v48, v48, v216, v64
	v_fma_f32 v49, v49, v216, v65
	v_fma_f32 v42, v42, v216, v58
	v_fma_f32 v43, v43, v216, v59
	v_fma_f32 v44, v44, v216, v60
	v_fma_f32 v45, v45, v216, v61
	v_mul_f32_e32 v190, 0xbfb8aa3b, v46
	v_mul_f32_e32 v191, 0xbfb8aa3b, v47
	v_mul_f32_e32 v192, 0xbfb8aa3b, v48
	v_mul_f32_e32 v193, 0xbfb8aa3b, v49
	v_mul_f32_e32 v194, 0xbfb8aa3b, v42
	v_mul_f32_e32 v195, 0xbfb8aa3b, v43
	v_mul_f32_e32 v196, 0xbfb8aa3b, v44
	v_mul_f32_e32 v197, 0xbfb8aa3b, v45
	v_fma_f32 v38, v38, v216, v54
	v_fma_f32 v39, v39, v216, v55
	v_fma_f32 v40, v40, v216, v56
	v_fma_f32 v41, v41, v216, v57
	v_fma_f32 v34, v34, v216, v50
	v_fma_f32 v35, v35, v216, v51
	v_fma_f32 v36, v36, v216, v52
	v_fma_f32 v37, v37, v216, v53
	v_exp_f32_e32 v190, v190
	v_exp_f32_e32 v191, v191
	v_exp_f32_e32 v192, v192
	v_exp_f32_e32 v193, v193
	v_exp_f32_e32 v194, v194
	v_exp_f32_e32 v195, v195
	v_exp_f32_e32 v196, v196
	v_exp_f32_e32 v197, v197
	v_add_u32_e32 v228, s11, v178
	v_mad_i64_i32 v[228:229], s[12:13], v228, s90, v[224:225]
	v_add_f32_e32 v190, 1.0, v190
	v_add_f32_e32 v191, 1.0, v191
	v_add_f32_e32 v192, 1.0, v192
	v_add_f32_e32 v193, 1.0, v193
	v_add_f32_e32 v194, 1.0, v194
	v_add_f32_e32 v195, 1.0, v195
	v_add_f32_e32 v196, 1.0, v196
	v_add_f32_e32 v197, 1.0, v197
	v_rcp_f32_e32 v190, v190
	v_rcp_f32_e32 v191, v191
	v_rcp_f32_e32 v192, v192
	v_rcp_f32_e32 v193, v193
	v_rcp_f32_e32 v194, v194
	v_rcp_f32_e32 v195, v195
	v_rcp_f32_e32 v196, v196
	v_rcp_f32_e32 v197, v197
	v_mul_f32_e32 v46, v46, v190
	v_mul_f32_e32 v47, v47, v191
	v_mul_f32_e32 v48, v48, v192
	v_mul_f32_e32 v49, v49, v193
	v_mul_f32_e32 v42, v42, v194
	v_mul_f32_e32 v43, v43, v195
	v_mul_f32_e32 v44, v44, v196
	v_mul_f32_e32 v45, v45, v197
	v_mul_f32_e32 v46, v38, v46
	v_mul_f32_e32 v47, v39, v47
	v_mul_f32_e32 v48, v40, v48
	v_mul_f32_e32 v49, v41, v49
	v_mul_f32_e32 v42, v34, v42
	v_mul_f32_e32 v43, v35, v43
	v_mul_f32_e32 v44, v36, v44
	v_mul_f32_e32 v45, v37, v45
	v_cvt_pk_bf16_f32 v202, v46, v47
	v_cvt_pk_bf16_f32 v203, v48, v49
	v_cvt_pk_bf16_f32 v204, v42, v43
	v_cvt_pk_bf16_f32 v205, v44, v45
	global_store_dwordx4 v[228:229], v[202:205], off
	v_fma_f32 v30, v30, v218, v62
	v_fma_f32 v31, v31, v218, v63
	v_fma_f32 v32, v32, v218, v64
	v_fma_f32 v33, v33, v218, v65
	v_fma_f32 v26, v26, v218, v58
	v_fma_f32 v27, v27, v218, v59
	v_fma_f32 v28, v28, v218, v60
	v_fma_f32 v29, v29, v218, v61
	v_mul_f32_e32 v190, 0xbfb8aa3b, v30
	v_mul_f32_e32 v191, 0xbfb8aa3b, v31
	v_mul_f32_e32 v192, 0xbfb8aa3b, v32
	v_mul_f32_e32 v193, 0xbfb8aa3b, v33
	v_mul_f32_e32 v194, 0xbfb8aa3b, v26
	v_mul_f32_e32 v195, 0xbfb8aa3b, v27
	v_mul_f32_e32 v196, 0xbfb8aa3b, v28
	v_mul_f32_e32 v197, 0xbfb8aa3b, v29
	v_fma_f32 v22, v22, v218, v54
	v_fma_f32 v23, v23, v218, v55
	v_fma_f32 v24, v24, v218, v56
	v_fma_f32 v25, v25, v218, v57
	v_fma_f32 v18, v18, v218, v50
	v_fma_f32 v19, v19, v218, v51
	v_fma_f32 v20, v20, v218, v52
	v_fma_f32 v21, v21, v218, v53
	v_exp_f32_e32 v190, v190
	v_exp_f32_e32 v191, v191
	v_exp_f32_e32 v192, v192
	v_exp_f32_e32 v193, v193
	v_exp_f32_e32 v194, v194
	v_exp_f32_e32 v195, v195
	v_exp_f32_e32 v196, v196
	v_exp_f32_e32 v197, v197
	v_add_u32_e32 v226, s11, v179
	v_mad_i64_i32 v[226:227], s[12:13], v226, s90, v[224:225]
	v_add_f32_e32 v190, 1.0, v190
	v_add_f32_e32 v191, 1.0, v191
	v_add_f32_e32 v192, 1.0, v192
	v_add_f32_e32 v193, 1.0, v193
	v_add_f32_e32 v194, 1.0, v194
	v_add_f32_e32 v195, 1.0, v195
	v_add_f32_e32 v196, 1.0, v196
	v_add_f32_e32 v197, 1.0, v197
	v_rcp_f32_e32 v190, v190
	v_rcp_f32_e32 v191, v191
	v_rcp_f32_e32 v192, v192
	v_rcp_f32_e32 v193, v193
	v_rcp_f32_e32 v194, v194
	v_rcp_f32_e32 v195, v195
	v_rcp_f32_e32 v196, v196
	v_rcp_f32_e32 v197, v197
	v_mul_f32_e32 v30, v30, v190
	v_mul_f32_e32 v31, v31, v191
	v_mul_f32_e32 v32, v32, v192
	v_mul_f32_e32 v33, v33, v193
	v_mul_f32_e32 v26, v26, v194
	v_mul_f32_e32 v27, v27, v195
	v_mul_f32_e32 v28, v28, v196
	v_mul_f32_e32 v29, v29, v197
	v_mul_f32_e32 v30, v22, v30
	v_mul_f32_e32 v31, v23, v31
	v_mul_f32_e32 v32, v24, v32
	v_mul_f32_e32 v33, v25, v33
	v_mul_f32_e32 v26, v18, v26
	v_mul_f32_e32 v27, v19, v27
	v_mul_f32_e32 v28, v20, v28
	v_mul_f32_e32 v29, v21, v29
	v_cvt_pk_bf16_f32 v198, v30, v31
	v_cvt_pk_bf16_f32 v199, v32, v33
	v_cvt_pk_bf16_f32 v200, v26, v27
	v_cvt_pk_bf16_f32 v201, v28, v29
	global_store_dwordx4 v[226:227], v[198:201], off
	v_fma_f32 v14, v14, v220, v62
	v_fma_f32 v15, v15, v220, v63
	v_fma_f32 v16, v16, v220, v64
	v_fma_f32 v17, v17, v220, v65
	v_fma_f32 v10, v10, v220, v58
	v_fma_f32 v11, v11, v220, v59
	v_fma_f32 v12, v12, v220, v60
	v_fma_f32 v13, v13, v220, v61
	v_mul_f32_e32 v190, 0xbfb8aa3b, v14
	v_mul_f32_e32 v191, 0xbfb8aa3b, v15
	v_mul_f32_e32 v192, 0xbfb8aa3b, v16
	v_mul_f32_e32 v193, 0xbfb8aa3b, v17
	v_mul_f32_e32 v194, 0xbfb8aa3b, v10
	v_mul_f32_e32 v195, 0xbfb8aa3b, v11
	v_mul_f32_e32 v196, 0xbfb8aa3b, v12
	v_mul_f32_e32 v197, 0xbfb8aa3b, v13
	v_fma_f32 v6, v6, v220, v54
	v_fma_f32 v7, v7, v220, v55
	v_fma_f32 v8, v8, v220, v56
	v_fma_f32 v9, v9, v220, v57
	v_fma_f32 v2, v2, v220, v50
	v_fma_f32 v3, v3, v220, v51
	v_fma_f32 v4, v4, v220, v52
	v_fma_f32 v5, v5, v220, v53
	v_exp_f32_e32 v190, v190
	v_exp_f32_e32 v191, v191
	v_exp_f32_e32 v192, v192
	v_exp_f32_e32 v193, v193
	v_exp_f32_e32 v194, v194
	v_exp_f32_e32 v195, v195
	v_exp_f32_e32 v196, v196
	v_exp_f32_e32 v197, v197
	v_add_u32_e32 v228, s11, v180
	v_mad_i64_i32 v[228:229], s[12:13], v228, s90, v[224:225]
	v_add_f32_e32 v190, 1.0, v190
	v_add_f32_e32 v191, 1.0, v191
	v_add_f32_e32 v192, 1.0, v192
	v_add_f32_e32 v193, 1.0, v193
	v_add_f32_e32 v194, 1.0, v194
	v_add_f32_e32 v195, 1.0, v195
	v_add_f32_e32 v196, 1.0, v196
	v_add_f32_e32 v197, 1.0, v197
	v_rcp_f32_e32 v190, v190
	v_rcp_f32_e32 v191, v191
	v_rcp_f32_e32 v192, v192
	v_rcp_f32_e32 v193, v193
	v_rcp_f32_e32 v194, v194
	v_rcp_f32_e32 v195, v195
	v_rcp_f32_e32 v196, v196
	v_rcp_f32_e32 v197, v197
	v_mul_f32_e32 v14, v14, v190
	v_mul_f32_e32 v15, v15, v191
	v_mul_f32_e32 v16, v16, v192
	v_mul_f32_e32 v17, v17, v193
	v_mul_f32_e32 v10, v10, v194
	v_mul_f32_e32 v11, v11, v195
	v_mul_f32_e32 v12, v12, v196
	v_mul_f32_e32 v13, v13, v197
	v_mul_f32_e32 v14, v6, v14
	v_mul_f32_e32 v15, v7, v15
	v_mul_f32_e32 v16, v8, v16
	v_mul_f32_e32 v17, v9, v17
	v_mul_f32_e32 v10, v2, v10
	v_mul_f32_e32 v11, v3, v11
	v_mul_f32_e32 v12, v4, v12
	v_mul_f32_e32 v13, v5, v13
	v_cvt_pk_bf16_f32 v202, v14, v15
	v_cvt_pk_bf16_f32 v203, v16, v17
	v_cvt_pk_bf16_f32 v204, v10, v11
	v_cvt_pk_bf16_f32 v205, v12, v13
	global_store_dwordx4 v[228:229], v[202:205], off
	s_cmp_gt_i32 s10, 63
	s_cselect_b64 s[0:1], -1, 0
	s_and_b64 s[0:1], s[72:73], s[0:1]
	s_andn2_b64 vcc, exec, s[0:1]
	s_cbranch_vccnz .LBB0_785
	s_waitcnt vmcnt(0)
	s_barrier
	s_mov_b64 s[0:1], exec
	v_readlane_b32 s10, v250, 4
	v_readlane_b32 s11, v250, 5
	s_and_b64 s[10:11], s[0:1], s[10:11]
	s_mov_b64 exec, s[10:11]
	s_cbranch_execz .LBB0_784
	s_mov_b64 s[10:11], exec
	v_mbcnt_lo_u32_b32 v2, s10, 0
	buffer_wbl2 sc1
	s_waitcnt vmcnt(0)
	s_waitcnt vmcnt(0)
	v_mbcnt_hi_u32_b32 v2, s11, v2
	v_cmp_eq_u32_e32 vcc, 0, v2
	s_and_b64 s[12:13], exec, vcc
	s_mov_b64 exec, s[12:13]
	s_cbranch_execz .LBB0_784
	s_bcnt1_i32_b64 s3, s[10:11]
	v_mov_b32_e32 v2, s3
	global_atomic_add v151, v2, s[6:7] offset:2816

.LBB0_1482:
	v_lshl_or_b32 v224, s42, 7, v175
	v_lshl_add_u32 v223, v1, 2, s41
	ds_read_b32 v206, v223
	ds_read_b32 v208, v223 offset:64
	ds_read_b32 v210, v223 offset:128
	ds_read_b32 v212, v223 offset:192
	ds_read_b32 v214, v223 offset:512
	ds_read_b32 v216, v223 offset:576
	ds_read_b32 v218, v223 offset:640
	ds_read_b32 v220, v223 offset:704
	s_lshl_b32 s0, s57, 2
	s_add_i32 s0, s41, s0
	v_lshl_add_u32 v222, v166, 2, s0
	s_lshl_b32 s12, s40, 8
	ds_read_b128 v[110:113], v222 offset:1024
	ds_read_b128 v[106:109], v222 offset:1040
	ds_read_b128 v[102:105], v222 offset:1536
	ds_read_b128 v[98:101], v222 offset:1552
	v_ashrrev_i32_e32 v225, 31, v224
	v_lshlrev_b64 v[224:225], 1, v[224:225]
	v_lshl_add_u64 v[224:225], s[10:11], 0, v[224:225]
	s_waitcnt lgkmcnt(4)
	v_fmamk_f32 v206, v206, 0x3a800000, v179
	v_fmamk_f32 v208, v208, 0x3a800000, v179
	v_fmamk_f32 v210, v210, 0x3a800000, v179
	v_fmamk_f32 v212, v212, 0x3a800000, v179
	v_fmamk_f32 v214, v214, 0x3a800000, v179
	v_fmamk_f32 v216, v216, 0x3a800000, v179
	v_fmamk_f32 v218, v218, 0x3a800000, v179
	v_fmamk_f32 v220, v220, 0x3a800000, v179
	v_rsq_f32_e32 v206, v206
	v_rsq_f32_e32 v208, v208
	v_rsq_f32_e32 v210, v210
	v_rsq_f32_e32 v212, v212
	v_rsq_f32_e32 v214, v214
	v_rsq_f32_e32 v216, v216
	v_rsq_f32_e32 v218, v218
	v_rsq_f32_e32 v220, v220
	s_waitcnt lgkmcnt(0)
	v_fma_f32 v142, v142, v206, v110
	v_fma_f32 v143, v143, v206, v111
	v_fma_f32 v144, v144, v206, v112
	v_fma_f32 v145, v145, v206, v113
	v_fma_f32 v138, v138, v206, v106
	v_fma_f32 v139, v139, v206, v107
	v_fma_f32 v140, v140, v206, v108
	v_fma_f32 v141, v141, v206, v109
	v_mul_f32_e32 v190, 0xbfb8aa3b, v142
	v_mul_f32_e32 v191, 0xbfb8aa3b, v143
	v_mul_f32_e32 v192, 0xbfb8aa3b, v144
	v_mul_f32_e32 v193, 0xbfb8aa3b, v145
	v_mul_f32_e32 v194, 0xbfb8aa3b, v138
	v_mul_f32_e32 v195, 0xbfb8aa3b, v139
	v_mul_f32_e32 v196, 0xbfb8aa3b, v140
	v_mul_f32_e32 v197, 0xbfb8aa3b, v141
	v_fma_f32 v134, v134, v206, v102
	v_fma_f32 v135, v135, v206, v103
	v_fma_f32 v136, v136, v206, v104
	v_fma_f32 v137, v137, v206, v105
	v_fma_f32 v130, v130, v206, v98
	v_fma_f32 v131, v131, v206, v99
	v_fma_f32 v132, v132, v206, v100
	v_fma_f32 v133, v133, v206, v101
	v_exp_f32_e32 v190, v190
	v_exp_f32_e32 v191, v191
	v_exp_f32_e32 v192, v192
	v_exp_f32_e32 v193, v193
	v_exp_f32_e32 v194, v194
	v_exp_f32_e32 v195, v195
	v_exp_f32_e32 v196, v196
	v_exp_f32_e32 v197, v197
	v_add_u32_e32 v226, s12, v1
	v_mad_i64_i32 v[226:227], s[0:1], v226, s63, v[224:225]
	v_add_f32_e32 v190, 1.0, v190
	v_add_f32_e32 v191, 1.0, v191
	v_add_f32_e32 v192, 1.0, v192
	v_add_f32_e32 v193, 1.0, v193
	v_add_f32_e32 v194, 1.0, v194
	v_add_f32_e32 v195, 1.0, v195
	v_add_f32_e32 v196, 1.0, v196
	v_add_f32_e32 v197, 1.0, v197
	v_rcp_f32_e32 v190, v190
	v_rcp_f32_e32 v191, v191
	v_rcp_f32_e32 v192, v192
	v_rcp_f32_e32 v193, v193
	v_rcp_f32_e32 v194, v194
	v_rcp_f32_e32 v195, v195
	v_rcp_f32_e32 v196, v196
	v_rcp_f32_e32 v197, v197
	v_mul_f32_e32 v142, v142, v190
	v_mul_f32_e32 v143, v143, v191
	v_mul_f32_e32 v144, v144, v192
	v_mul_f32_e32 v145, v145, v193
	v_mul_f32_e32 v138, v138, v194
	v_mul_f32_e32 v139, v139, v195
	v_mul_f32_e32 v140, v140, v196
	v_mul_f32_e32 v141, v141, v197
	v_mul_f32_e32 v142, v134, v142
	v_mul_f32_e32 v143, v135, v143
	v_mul_f32_e32 v144, v136, v144
	v_mul_f32_e32 v145, v137, v145
	v_mul_f32_e32 v138, v130, v138
	v_mul_f32_e32 v139, v131, v139
	v_mul_f32_e32 v140, v132, v140
	v_mul_f32_e32 v141, v133, v141
	v_cvt_pk_bf16_f32 v198, v142, v143
	v_cvt_pk_bf16_f32 v199, v144, v145
	v_cvt_pk_bf16_f32 v200, v138, v139
	v_cvt_pk_bf16_f32 v201, v140, v141
	global_store_dwordx4 v[226:227], v[198:201], off
	v_fma_f32 v126, v126, v208, v110
	v_fma_f32 v127, v127, v208, v111
	v_fma_f32 v128, v128, v208, v112
	v_fma_f32 v129, v129, v208, v113
	v_fma_f32 v122, v122, v208, v106
	v_fma_f32 v123, v123, v208, v107
	v_fma_f32 v124, v124, v208, v108
	v_fma_f32 v125, v125, v208, v109
	v_mul_f32_e32 v190, 0xbfb8aa3b, v126
	v_mul_f32_e32 v191, 0xbfb8aa3b, v127
	v_mul_f32_e32 v192, 0xbfb8aa3b, v128
	v_mul_f32_e32 v193, 0xbfb8aa3b, v129
	v_mul_f32_e32 v194, 0xbfb8aa3b, v122
	v_mul_f32_e32 v195, 0xbfb8aa3b, v123
	v_mul_f32_e32 v196, 0xbfb8aa3b, v124
	v_mul_f32_e32 v197, 0xbfb8aa3b, v125
	v_fma_f32 v118, v118, v208, v102
	v_fma_f32 v119, v119, v208, v103
	v_fma_f32 v120, v120, v208, v104
	v_fma_f32 v121, v121, v208, v105
	v_fma_f32 v114, v114, v208, v98
	v_fma_f32 v115, v115, v208, v99
	v_fma_f32 v116, v116, v208, v100
	v_fma_f32 v117, v117, v208, v101
	v_exp_f32_e32 v190, v190
	v_exp_f32_e32 v191, v191
	v_exp_f32_e32 v192, v192
	v_exp_f32_e32 v193, v193
	v_exp_f32_e32 v194, v194
	v_exp_f32_e32 v195, v195
	v_exp_f32_e32 v196, v196
	v_exp_f32_e32 v197, v197
	v_add_u32_e32 v228, s12, v168
	v_mad_i64_i32 v[228:229], s[0:1], v228, s63, v[224:225]
	v_add_f32_e32 v190, 1.0, v190
	v_add_f32_e32 v191, 1.0, v191
	v_add_f32_e32 v192, 1.0, v192
	v_add_f32_e32 v193, 1.0, v193
	v_add_f32_e32 v194, 1.0, v194
	v_add_f32_e32 v195, 1.0, v195
	v_add_f32_e32 v196, 1.0, v196
	v_add_f32_e32 v197, 1.0, v197
	v_rcp_f32_e32 v190, v190
	v_rcp_f32_e32 v191, v191
	v_rcp_f32_e32 v192, v192
	v_rcp_f32_e32 v193, v193
	v_rcp_f32_e32 v194, v194
	v_rcp_f32_e32 v195, v195
	v_rcp_f32_e32 v196, v196
	v_rcp_f32_e32 v197, v197
	v_mul_f32_e32 v126, v126, v190
	v_mul_f32_e32 v127, v127, v191
	v_mul_f32_e32 v128, v128, v192
	v_mul_f32_e32 v129, v129, v193
	v_mul_f32_e32 v122, v122, v194
	v_mul_f32_e32 v123, v123, v195
	v_mul_f32_e32 v124, v124, v196
	v_mul_f32_e32 v125, v125, v197
	v_mul_f32_e32 v126, v118, v126
	v_mul_f32_e32 v127, v119, v127
	v_mul_f32_e32 v128, v120, v128
	v_mul_f32_e32 v129, v121, v129
	v_mul_f32_e32 v122, v114, v122
	v_mul_f32_e32 v123, v115, v123
	v_mul_f32_e32 v124, v116, v124
	v_mul_f32_e32 v125, v117, v125
	v_cvt_pk_bf16_f32 v202, v126, v127
	v_cvt_pk_bf16_f32 v203, v128, v129
	v_cvt_pk_bf16_f32 v204, v122, v123
	v_cvt_pk_bf16_f32 v205, v124, v125
	global_store_dwordx4 v[228:229], v[202:205], off
	v_fma_f32 v94, v94, v210, v110
	v_fma_f32 v95, v95, v210, v111
	v_fma_f32 v96, v96, v210, v112
	v_fma_f32 v97, v97, v210, v113
	v_fma_f32 v90, v90, v210, v106
	v_fma_f32 v91, v91, v210, v107
	v_fma_f32 v92, v92, v210, v108
	v_fma_f32 v93, v93, v210, v109
	v_mul_f32_e32 v190, 0xbfb8aa3b, v94
	v_mul_f32_e32 v191, 0xbfb8aa3b, v95
	v_mul_f32_e32 v192, 0xbfb8aa3b, v96
	v_mul_f32_e32 v193, 0xbfb8aa3b, v97
	v_mul_f32_e32 v194, 0xbfb8aa3b, v90
	v_mul_f32_e32 v195, 0xbfb8aa3b, v91
	v_mul_f32_e32 v196, 0xbfb8aa3b, v92
	v_mul_f32_e32 v197, 0xbfb8aa3b, v93
	v_fma_f32 v86, v86, v210, v102
	v_fma_f32 v87, v87, v210, v103
	v_fma_f32 v88, v88, v210, v104
	v_fma_f32 v89, v89, v210, v105
	v_fma_f32 v82, v82, v210, v98
	v_fma_f32 v83, v83, v210, v99
	v_fma_f32 v84, v84, v210, v100
	v_fma_f32 v85, v85, v210, v101
	v_exp_f32_e32 v190, v190
	v_exp_f32_e32 v191, v191
	v_exp_f32_e32 v192, v192
	v_exp_f32_e32 v193, v193
	v_exp_f32_e32 v194, v194
	v_exp_f32_e32 v195, v195
	v_exp_f32_e32 v196, v196
	v_exp_f32_e32 v197, v197
	v_add_u32_e32 v226, s12, v169
	v_mad_i64_i32 v[226:227], s[0:1], v226, s63, v[224:225]
	v_add_f32_e32 v190, 1.0, v190
	v_add_f32_e32 v191, 1.0, v191
	v_add_f32_e32 v192, 1.0, v192
	v_add_f32_e32 v193, 1.0, v193
	v_add_f32_e32 v194, 1.0, v194
	v_add_f32_e32 v195, 1.0, v195
	v_add_f32_e32 v196, 1.0, v196
	v_add_f32_e32 v197, 1.0, v197
	v_rcp_f32_e32 v190, v190
	v_rcp_f32_e32 v191, v191
	v_rcp_f32_e32 v192, v192
	v_rcp_f32_e32 v193, v193
	v_rcp_f32_e32 v194, v194
	v_rcp_f32_e32 v195, v195
	v_rcp_f32_e32 v196, v196
	v_rcp_f32_e32 v197, v197
	v_mul_f32_e32 v94, v94, v190
	v_mul_f32_e32 v95, v95, v191
	v_mul_f32_e32 v96, v96, v192
	v_mul_f32_e32 v97, v97, v193
	v_mul_f32_e32 v90, v90, v194
	v_mul_f32_e32 v91, v91, v195
	v_mul_f32_e32 v92, v92, v196
	v_mul_f32_e32 v93, v93, v197
	v_mul_f32_e32 v94, v86, v94
	v_mul_f32_e32 v95, v87, v95
	v_mul_f32_e32 v96, v88, v96
	v_mul_f32_e32 v97, v89, v97
	v_mul_f32_e32 v90, v82, v90
	v_mul_f32_e32 v91, v83, v91
	v_mul_f32_e32 v92, v84, v92
	v_mul_f32_e32 v93, v85, v93
	v_cvt_pk_bf16_f32 v198, v94, v95
	v_cvt_pk_bf16_f32 v199, v96, v97
	v_cvt_pk_bf16_f32 v200, v90, v91
	v_cvt_pk_bf16_f32 v201, v92, v93
	global_store_dwordx4 v[226:227], v[198:201], off
	v_fma_f32 v78, v78, v212, v110
	v_fma_f32 v79, v79, v212, v111
	v_fma_f32 v80, v80, v212, v112
	v_fma_f32 v81, v81, v212, v113
	v_fma_f32 v74, v74, v212, v106
	v_fma_f32 v75, v75, v212, v107
	v_fma_f32 v76, v76, v212, v108
	v_fma_f32 v77, v77, v212, v109
	v_mul_f32_e32 v190, 0xbfb8aa3b, v78
	v_mul_f32_e32 v191, 0xbfb8aa3b, v79
	v_mul_f32_e32 v192, 0xbfb8aa3b, v80
	v_mul_f32_e32 v193, 0xbfb8aa3b, v81
	v_mul_f32_e32 v194, 0xbfb8aa3b, v74
	v_mul_f32_e32 v195, 0xbfb8aa3b, v75
	v_mul_f32_e32 v196, 0xbfb8aa3b, v76
	v_mul_f32_e32 v197, 0xbfb8aa3b, v77
	v_fma_f32 v70, v70, v212, v102
	v_fma_f32 v71, v71, v212, v103
	v_fma_f32 v72, v72, v212, v104
	v_fma_f32 v73, v73, v212, v105
	v_fma_f32 v66, v66, v212, v98
	v_fma_f32 v67, v67, v212, v99
	v_fma_f32 v68, v68, v212, v100
	v_fma_f32 v69, v69, v212, v101
	v_exp_f32_e32 v190, v190
	v_exp_f32_e32 v191, v191
	v_exp_f32_e32 v192, v192
	v_exp_f32_e32 v193, v193
	v_exp_f32_e32 v194, v194
	v_exp_f32_e32 v195, v195
	v_exp_f32_e32 v196, v196
	v_exp_f32_e32 v197, v197
	v_add_u32_e32 v228, s12, v170
	v_mad_i64_i32 v[228:229], s[0:1], v228, s63, v[224:225]
	v_add_f32_e32 v190, 1.0, v190
	v_add_f32_e32 v191, 1.0, v191
	v_add_f32_e32 v192, 1.0, v192
	v_add_f32_e32 v193, 1.0, v193
	v_add_f32_e32 v194, 1.0, v194
	v_add_f32_e32 v195, 1.0, v195
	v_add_f32_e32 v196, 1.0, v196
	v_add_f32_e32 v197, 1.0, v197
	v_rcp_f32_e32 v190, v190
	v_rcp_f32_e32 v191, v191
	v_rcp_f32_e32 v192, v192
	v_rcp_f32_e32 v193, v193
	v_rcp_f32_e32 v194, v194
	v_rcp_f32_e32 v195, v195
	v_rcp_f32_e32 v196, v196
	v_rcp_f32_e32 v197, v197
	v_mul_f32_e32 v78, v78, v190
	v_mul_f32_e32 v79, v79, v191
	v_mul_f32_e32 v80, v80, v192
	v_mul_f32_e32 v81, v81, v193
	v_mul_f32_e32 v74, v74, v194
	v_mul_f32_e32 v75, v75, v195
	v_mul_f32_e32 v76, v76, v196
	v_mul_f32_e32 v77, v77, v197
	v_mul_f32_e32 v78, v70, v78
	v_mul_f32_e32 v79, v71, v79
	v_mul_f32_e32 v80, v72, v80
	v_mul_f32_e32 v81, v73, v81
	v_mul_f32_e32 v74, v66, v74
	v_mul_f32_e32 v75, v67, v75
	v_mul_f32_e32 v76, v68, v76
	v_mul_f32_e32 v77, v69, v77
	v_cvt_pk_bf16_f32 v202, v78, v79
	v_cvt_pk_bf16_f32 v203, v80, v81
	v_cvt_pk_bf16_f32 v204, v74, v75
	v_cvt_pk_bf16_f32 v205, v76, v77
	global_store_dwordx4 v[228:229], v[202:205], off
	v_fma_f32 v62, v62, v214, v110
	v_fma_f32 v63, v63, v214, v111
	v_fma_f32 v64, v64, v214, v112
	v_fma_f32 v65, v65, v214, v113
	v_fma_f32 v58, v58, v214, v106
	v_fma_f32 v59, v59, v214, v107
	v_fma_f32 v60, v60, v214, v108
	v_fma_f32 v61, v61, v214, v109
	v_mul_f32_e32 v190, 0xbfb8aa3b, v62
	v_mul_f32_e32 v191, 0xbfb8aa3b, v63
	v_mul_f32_e32 v192, 0xbfb8aa3b, v64
	v_mul_f32_e32 v193, 0xbfb8aa3b, v65
	v_mul_f32_e32 v194, 0xbfb8aa3b, v58
	v_mul_f32_e32 v195, 0xbfb8aa3b, v59
	v_mul_f32_e32 v196, 0xbfb8aa3b, v60
	v_mul_f32_e32 v197, 0xbfb8aa3b, v61
	v_fma_f32 v54, v54, v214, v102
	v_fma_f32 v55, v55, v214, v103
	v_fma_f32 v56, v56, v214, v104
	v_fma_f32 v57, v57, v214, v105
	v_fma_f32 v50, v50, v214, v98
	v_fma_f32 v51, v51, v214, v99
	v_fma_f32 v52, v52, v214, v100
	v_fma_f32 v53, v53, v214, v101
	v_exp_f32_e32 v190, v190
	v_exp_f32_e32 v191, v191
	v_exp_f32_e32 v192, v192
	v_exp_f32_e32 v193, v193
	v_exp_f32_e32 v194, v194
	v_exp_f32_e32 v195, v195
	v_exp_f32_e32 v196, v196
	v_exp_f32_e32 v197, v197
	v_add_u32_e32 v226, s12, v171
	v_mad_i64_i32 v[226:227], s[0:1], v226, s63, v[224:225]
	v_add_f32_e32 v190, 1.0, v190
	v_add_f32_e32 v191, 1.0, v191
	v_add_f32_e32 v192, 1.0, v192
	v_add_f32_e32 v193, 1.0, v193
	v_add_f32_e32 v194, 1.0, v194
	v_add_f32_e32 v195, 1.0, v195
	v_add_f32_e32 v196, 1.0, v196
	v_add_f32_e32 v197, 1.0, v197
	v_rcp_f32_e32 v190, v190
	v_rcp_f32_e32 v191, v191
	v_rcp_f32_e32 v192, v192
	v_rcp_f32_e32 v193, v193
	v_rcp_f32_e32 v194, v194
	v_rcp_f32_e32 v195, v195
	v_rcp_f32_e32 v196, v196
	v_rcp_f32_e32 v197, v197
	v_mul_f32_e32 v62, v62, v190
	v_mul_f32_e32 v63, v63, v191
	v_mul_f32_e32 v64, v64, v192
	v_mul_f32_e32 v65, v65, v193
	v_mul_f32_e32 v58, v58, v194
	v_mul_f32_e32 v59, v59, v195
	v_mul_f32_e32 v60, v60, v196
	v_mul_f32_e32 v61, v61, v197
	v_mul_f32_e32 v62, v54, v62
	v_mul_f32_e32 v63, v55, v63
	v_mul_f32_e32 v64, v56, v64
	v_mul_f32_e32 v65, v57, v65
	v_mul_f32_e32 v58, v50, v58
	v_mul_f32_e32 v59, v51, v59
	v_mul_f32_e32 v60, v52, v60
	v_mul_f32_e32 v61, v53, v61
	v_cvt_pk_bf16_f32 v198, v62, v63
	v_cvt_pk_bf16_f32 v199, v64, v65
	v_cvt_pk_bf16_f32 v200, v58, v59
	v_cvt_pk_bf16_f32 v201, v60, v61
	global_store_dwordx4 v[226:227], v[198:201], off
	v_fma_f32 v46, v46, v216, v110
	v_fma_f32 v47, v47, v216, v111
	v_fma_f32 v48, v48, v216, v112
	v_fma_f32 v49, v49, v216, v113
	v_fma_f32 v42, v42, v216, v106
	v_fma_f32 v43, v43, v216, v107
	v_fma_f32 v44, v44, v216, v108
	v_fma_f32 v45, v45, v216, v109
	v_mul_f32_e32 v190, 0xbfb8aa3b, v46
	v_mul_f32_e32 v191, 0xbfb8aa3b, v47
	v_mul_f32_e32 v192, 0xbfb8aa3b, v48
	v_mul_f32_e32 v193, 0xbfb8aa3b, v49
	v_mul_f32_e32 v194, 0xbfb8aa3b, v42
	v_mul_f32_e32 v195, 0xbfb8aa3b, v43
	v_mul_f32_e32 v196, 0xbfb8aa3b, v44
	v_mul_f32_e32 v197, 0xbfb8aa3b, v45
	v_fma_f32 v38, v38, v216, v102
	v_fma_f32 v39, v39, v216, v103
	v_fma_f32 v40, v40, v216, v104
	v_fma_f32 v41, v41, v216, v105
	v_fma_f32 v34, v34, v216, v98
	v_fma_f32 v35, v35, v216, v99
	v_fma_f32 v36, v36, v216, v100
	v_fma_f32 v37, v37, v216, v101
	v_exp_f32_e32 v190, v190
	v_exp_f32_e32 v191, v191
	v_exp_f32_e32 v192, v192
	v_exp_f32_e32 v193, v193
	v_exp_f32_e32 v194, v194
	v_exp_f32_e32 v195, v195
	v_exp_f32_e32 v196, v196
	v_exp_f32_e32 v197, v197
	v_add_u32_e32 v228, s12, v172
	v_mad_i64_i32 v[228:229], s[0:1], v228, s63, v[224:225]
	v_add_f32_e32 v190, 1.0, v190
	v_add_f32_e32 v191, 1.0, v191
	v_add_f32_e32 v192, 1.0, v192
	v_add_f32_e32 v193, 1.0, v193
	v_add_f32_e32 v194, 1.0, v194
	v_add_f32_e32 v195, 1.0, v195
	v_add_f32_e32 v196, 1.0, v196
	v_add_f32_e32 v197, 1.0, v197
	v_rcp_f32_e32 v190, v190
	v_rcp_f32_e32 v191, v191
	v_rcp_f32_e32 v192, v192
	v_rcp_f32_e32 v193, v193
	v_rcp_f32_e32 v194, v194
	v_rcp_f32_e32 v195, v195
	v_rcp_f32_e32 v196, v196
	v_rcp_f32_e32 v197, v197
	v_mul_f32_e32 v46, v46, v190
	v_mul_f32_e32 v47, v47, v191
	v_mul_f32_e32 v48, v48, v192
	v_mul_f32_e32 v49, v49, v193
	v_mul_f32_e32 v42, v42, v194
	v_mul_f32_e32 v43, v43, v195
	v_mul_f32_e32 v44, v44, v196
	v_mul_f32_e32 v45, v45, v197
	v_mul_f32_e32 v46, v38, v46
	v_mul_f32_e32 v47, v39, v47
	v_mul_f32_e32 v48, v40, v48
	v_mul_f32_e32 v49, v41, v49
	v_mul_f32_e32 v42, v34, v42
	v_mul_f32_e32 v43, v35, v43
	v_mul_f32_e32 v44, v36, v44
	v_mul_f32_e32 v45, v37, v45
	v_cvt_pk_bf16_f32 v202, v46, v47
	v_cvt_pk_bf16_f32 v203, v48, v49
	v_cvt_pk_bf16_f32 v204, v42, v43
	v_cvt_pk_bf16_f32 v205, v44, v45
	global_store_dwordx4 v[228:229], v[202:205], off
	v_fma_f32 v30, v30, v218, v110
	v_fma_f32 v31, v31, v218, v111
	v_fma_f32 v32, v32, v218, v112
	v_fma_f32 v33, v33, v218, v113
	v_fma_f32 v26, v26, v218, v106
	v_fma_f32 v27, v27, v218, v107
	v_fma_f32 v28, v28, v218, v108
	v_fma_f32 v29, v29, v218, v109
	v_mul_f32_e32 v190, 0xbfb8aa3b, v30
	v_mul_f32_e32 v191, 0xbfb8aa3b, v31
	v_mul_f32_e32 v192, 0xbfb8aa3b, v32
	v_mul_f32_e32 v193, 0xbfb8aa3b, v33
	v_mul_f32_e32 v194, 0xbfb8aa3b, v26
	v_mul_f32_e32 v195, 0xbfb8aa3b, v27
	v_mul_f32_e32 v196, 0xbfb8aa3b, v28
	v_mul_f32_e32 v197, 0xbfb8aa3b, v29
	v_fma_f32 v22, v22, v218, v102
	v_fma_f32 v23, v23, v218, v103
	v_fma_f32 v24, v24, v218, v104
	v_fma_f32 v25, v25, v218, v105
	v_fma_f32 v18, v18, v218, v98
	v_fma_f32 v19, v19, v218, v99
	v_fma_f32 v20, v20, v218, v100
	v_fma_f32 v21, v21, v218, v101
	v_exp_f32_e32 v190, v190
	v_exp_f32_e32 v191, v191
	v_exp_f32_e32 v192, v192
	v_exp_f32_e32 v193, v193
	v_exp_f32_e32 v194, v194
	v_exp_f32_e32 v195, v195
	v_exp_f32_e32 v196, v196
	v_exp_f32_e32 v197, v197
	v_add_u32_e32 v226, s12, v173
	v_mad_i64_i32 v[226:227], s[0:1], v226, s63, v[224:225]
	v_add_f32_e32 v190, 1.0, v190
	v_add_f32_e32 v191, 1.0, v191
	v_add_f32_e32 v192, 1.0, v192
	v_add_f32_e32 v193, 1.0, v193
	v_add_f32_e32 v194, 1.0, v194
	v_add_f32_e32 v195, 1.0, v195
	v_add_f32_e32 v196, 1.0, v196
	v_add_f32_e32 v197, 1.0, v197
	v_rcp_f32_e32 v190, v190
	v_rcp_f32_e32 v191, v191
	v_rcp_f32_e32 v192, v192
	v_rcp_f32_e32 v193, v193
	v_rcp_f32_e32 v194, v194
	v_rcp_f32_e32 v195, v195
	v_rcp_f32_e32 v196, v196
	v_rcp_f32_e32 v197, v197
	v_mul_f32_e32 v30, v30, v190
	v_mul_f32_e32 v31, v31, v191
	v_mul_f32_e32 v32, v32, v192
	v_mul_f32_e32 v33, v33, v193
	v_mul_f32_e32 v26, v26, v194
	v_mul_f32_e32 v27, v27, v195
	v_mul_f32_e32 v28, v28, v196
	v_mul_f32_e32 v29, v29, v197
	v_mul_f32_e32 v30, v22, v30
	v_mul_f32_e32 v31, v23, v31
	v_mul_f32_e32 v32, v24, v32
	v_mul_f32_e32 v33, v25, v33
	v_mul_f32_e32 v26, v18, v26
	v_mul_f32_e32 v27, v19, v27
	v_mul_f32_e32 v28, v20, v28
	v_mul_f32_e32 v29, v21, v29
	v_cvt_pk_bf16_f32 v198, v30, v31
	v_cvt_pk_bf16_f32 v199, v32, v33
	v_cvt_pk_bf16_f32 v200, v26, v27
	v_cvt_pk_bf16_f32 v201, v28, v29
	global_store_dwordx4 v[226:227], v[198:201], off
	v_fma_f32 v14, v14, v220, v110
	v_fma_f32 v15, v15, v220, v111
	v_fma_f32 v16, v16, v220, v112
	v_fma_f32 v17, v17, v220, v113
	v_fma_f32 v10, v10, v220, v106
	v_fma_f32 v11, v11, v220, v107
	v_fma_f32 v12, v12, v220, v108
	v_fma_f32 v13, v13, v220, v109
	v_mul_f32_e32 v190, 0xbfb8aa3b, v14
	v_mul_f32_e32 v191, 0xbfb8aa3b, v15
	v_mul_f32_e32 v192, 0xbfb8aa3b, v16
	v_mul_f32_e32 v193, 0xbfb8aa3b, v17
	v_mul_f32_e32 v194, 0xbfb8aa3b, v10
	v_mul_f32_e32 v195, 0xbfb8aa3b, v11
	v_mul_f32_e32 v196, 0xbfb8aa3b, v12
	v_mul_f32_e32 v197, 0xbfb8aa3b, v13
	v_fma_f32 v6, v6, v220, v102
	v_fma_f32 v7, v7, v220, v103
	v_fma_f32 v8, v8, v220, v104
	v_fma_f32 v9, v9, v220, v105
	v_fma_f32 v2, v2, v220, v98
	v_fma_f32 v3, v3, v220, v99
	v_fma_f32 v4, v4, v220, v100
	v_fma_f32 v5, v5, v220, v101
	v_exp_f32_e32 v190, v190
	v_exp_f32_e32 v191, v191
	v_exp_f32_e32 v192, v192
	v_exp_f32_e32 v193, v193
	v_exp_f32_e32 v194, v194
	v_exp_f32_e32 v195, v195
	v_exp_f32_e32 v196, v196
	v_exp_f32_e32 v197, v197
	v_add_u32_e32 v228, s12, v174
	v_mad_i64_i32 v[228:229], s[0:1], v228, s63, v[224:225]
	v_add_f32_e32 v190, 1.0, v190
	v_add_f32_e32 v191, 1.0, v191
	v_add_f32_e32 v192, 1.0, v192
	v_add_f32_e32 v193, 1.0, v193
	v_add_f32_e32 v194, 1.0, v194
	v_add_f32_e32 v195, 1.0, v195
	v_add_f32_e32 v196, 1.0, v196
	v_add_f32_e32 v197, 1.0, v197
	v_rcp_f32_e32 v190, v190
	v_rcp_f32_e32 v191, v191
	v_rcp_f32_e32 v192, v192
	v_rcp_f32_e32 v193, v193
	v_rcp_f32_e32 v194, v194
	v_rcp_f32_e32 v195, v195
	v_rcp_f32_e32 v196, v196
	v_rcp_f32_e32 v197, v197
	v_mul_f32_e32 v14, v14, v190
	v_mul_f32_e32 v15, v15, v191
	v_mul_f32_e32 v16, v16, v192
	v_mul_f32_e32 v17, v17, v193
	v_mul_f32_e32 v10, v10, v194
	v_mul_f32_e32 v11, v11, v195
	v_mul_f32_e32 v12, v12, v196
	v_mul_f32_e32 v13, v13, v197
	v_mul_f32_e32 v14, v6, v14
	v_mul_f32_e32 v15, v7, v15
	v_mul_f32_e32 v16, v8, v16
	v_mul_f32_e32 v17, v9, v17
	v_mul_f32_e32 v10, v2, v10
	v_mul_f32_e32 v11, v3, v11
	v_mul_f32_e32 v12, v4, v12
	v_mul_f32_e32 v13, v5, v13
	v_cvt_pk_bf16_f32 v202, v14, v15
	v_cvt_pk_bf16_f32 v203, v16, v17
	v_cvt_pk_bf16_f32 v204, v10, v11
	v_cvt_pk_bf16_f32 v205, v12, v13
	global_store_dwordx4 v[228:229], v[202:205], off
	s_andn2_b64 vcc, exec, s[4:5]
	s_mov_b64 s[0:1], -1
	s_cbranch_vccnz .LBB0_1471
	s_andn2_b64 vcc, exec, s[8:9]
	s_cbranch_vccnz .LBB0_1470
	s_barrier
	s_branch .LBB0_1470

	.amdhsa_kernel _Z14fwd_megakernel4Args
		.amdhsa_group_segment_fixed_size 0
		.amdhsa_private_segment_fixed_size 0
		.amdhsa_kernarg_size 448
		.amdhsa_user_sgpr_count 2
		.amdhsa_user_sgpr_dispatch_ptr 0
		.amdhsa_user_sgpr_queue_ptr 0
		.amdhsa_user_sgpr_kernarg_segment_ptr 1
		.amdhsa_user_sgpr_dispatch_id 0
		.amdhsa_user_sgpr_kernarg_preload_length 0
		.amdhsa_user_sgpr_kernarg_preload_offset 0
		.amdhsa_user_sgpr_private_segment_size 0
		.amdhsa_uses_dynamic_stack 0
		.amdhsa_enable_private_segment 0
		.amdhsa_system_sgpr_workgroup_id_x 1
		.amdhsa_system_sgpr_workgroup_id_y 0
		.amdhsa_system_sgpr_workgroup_id_z 0
		.amdhsa_system_sgpr_workgroup_info 0
		.amdhsa_system_vgpr_workitem_id 0
		.amdhsa_next_free_vgpr 256
		.amdhsa_next_free_sgpr 102
		.amdhsa_accum_offset 256
		.amdhsa_reserve_vcc 1
		.amdhsa_float_round_mode_32 0
		.amdhsa_float_round_mode_16_64 0
		.amdhsa_float_denorm_mode_32 3
		.amdhsa_float_denorm_mode_16_64 3
		.amdhsa_dx10_clamp 1
		.amdhsa_ieee_mode 1
		.amdhsa_fp16_overflow 0
		.amdhsa_tg_split 0
		.amdhsa_exception_fp_ieee_invalid_op 0
		.amdhsa_exception_fp_denorm_src 0
		.amdhsa_exception_fp_ieee_div_zero 0
		.amdhsa_exception_fp_ieee_overflow 0
		.amdhsa_exception_fp_ieee_underflow 0
		.amdhsa_exception_fp_ieee_inexact 0
		.amdhsa_exception_int_div_zero 0
	.end_amdhsa_kernel

amdhsa.kernels:
  - .agpr_count:     0
    .args:
      - .offset:         0
        .size:           192
        .value_kind:     by_value
      - .offset:         192
        .size:           4
        .value_kind:     hidden_block_count_x
      - .offset:         196
        .size:           4
        .value_kind:     hidden_block_count_y
      - .offset:         200
        .size:           4
        .value_kind:     hidden_block_count_z
      - .offset:         204
        .size:           2
        .value_kind:     hidden_group_size_x
      - .offset:         206
        .size:           2
        .value_kind:     hidden_group_size_y
      - .offset:         208
        .size:           2
        .value_kind:     hidden_group_size_z
      - .offset:         210
        .size:           2
        .value_kind:     hidden_remainder_x
      - .offset:         212
        .size:           2
        .value_kind:     hidden_remainder_y
      - .offset:         214
        .size:           2
        .value_kind:     hidden_remainder_z
      - .offset:         232
        .size:           8
        .value_kind:     hidden_global_offset_x
      - .offset:         240
        .size:           8
        .value_kind:     hidden_global_offset_y
      - .offset:         248
        .size:           8
        .value_kind:     hidden_global_offset_z
      - .offset:         256
        .size:           2
        .value_kind:     hidden_grid_dims
      - .offset:         312
        .size:           4
        .value_kind:     hidden_dynamic_lds_size
    .group_segment_fixed_size: 0
    .kernarg_segment_align: 8
    .kernarg_segment_size: 448
    .language:       OpenCL C
    .language_version:
      - 2
      - 0
    .max_flat_workgroup_size: 512
    .name:           _Z14fwd_megakernel4Args
    .private_segment_fixed_size: 0
    .sgpr_count:     108
    .sgpr_spill_count: 27
    .symbol:         _Z14fwd_megakernel4Args.kd
    .uniform_work_group_size: 1
    .uses_dynamic_stack: false
    .vgpr_count:     256
    .vgpr_spill_count: 0
    .wavefront_size: 64
